# P6 K-loop: first 4 MFMAs of each compute block issued before the block's opening barrier (fills the matrix pipe during the barrier hand-off); on top of v9
# baseline (speedup 1.0000x reference)
.LBB0_731:
	ds_read_b128 v[148:151], v156
	ds_read_b128 v[160:163], v156 offset:1024
	ds_read_b128 v[164:167], v156 offset:2048
	ds_read_b128 v[168:171], v156 offset:3072
	ds_read_b128 v[176:179], v157
	ds_read_b128 v[180:183], v157 offset:1024
	ds_read_b128 v[184:187], v157 offset:2048
	ds_read_b128 v[188:191], v157 offset:3072
	s_add_u32 s22, s0, 0xfff00080
	s_addc_u32 s23, s1, -1
	s_cmp_eq_u32 s61, 60
	s_cselect_b32 s25, s5, s23
	s_cselect_b32 s24, s57, s22
	s_cselect_b32 s23, s21, s60
	s_cselect_b32 s22, s58, s59
	v_lshl_add_u64 v[152:153], s[0:1], 0, v[140:141]
	s_add_i32 m0, s34, 0xc000
	ds_read_b128 v[192:195], v158
	ds_read_b128 v[196:199], v158 offset:1024
	ds_read_b128 v[200:203], v158 offset:2048
	ds_read_b128 v[204:207], v158 offset:3072
	ds_read_b128 v[208:211], v158 offset:4096
	ds_read_b128 v[212:215], v158 offset:5120
	ds_read_b128 v[216:219], v158 offset:6144
	ds_read_b128 v[220:223], v158 offset:7168
	global_load_lds_dwordx4 v[152:153], off
	v_lshl_add_u64 v[152:153], s[0:1], 0, v[142:143]
	s_add_i32 m0, s34, 0xe000
	s_nop 0
	global_load_lds_dwordx4 v[152:153], off
	s_waitcnt lgkmcnt(0)
	v_mfma_f32_16x16x32_bf16 v[126:129], v[148:151], v[192:195], v[126:129]
	v_mfma_f32_16x16x32_bf16 v[122:125], v[164:167], v[192:195], v[122:125]
	v_mfma_f32_16x16x32_bf16 v[110:113], v[148:151], v[200:203], v[110:113]
	v_mfma_f32_16x16x32_bf16 v[106:109], v[164:167], v[200:203], v[106:109]
	s_waitcnt vmcnt(8)
	s_barrier
	s_setprio 1
	v_mfma_f32_16x16x32_bf16 v[94:97], v[148:151], v[208:211], v[94:97]
	v_mfma_f32_16x16x32_bf16 v[90:93], v[164:167], v[208:211], v[90:93]
	v_mfma_f32_16x16x32_bf16 v[78:81], v[148:151], v[216:219], v[78:81]
	v_mfma_f32_16x16x32_bf16 v[74:77], v[164:167], v[216:219], v[74:77]
	v_mfma_f32_16x16x32_bf16 v[126:129], v[160:163], v[196:199], v[126:129]
	v_mfma_f32_16x16x32_bf16 v[122:125], v[168:171], v[196:199], v[122:125]
	v_mfma_f32_16x16x32_bf16 v[110:113], v[160:163], v[204:207], v[110:113]
	v_mfma_f32_16x16x32_bf16 v[106:109], v[168:171], v[204:207], v[106:109]
	v_mfma_f32_16x16x32_bf16 v[94:97], v[160:163], v[212:215], v[94:97]
	v_mfma_f32_16x16x32_bf16 v[90:93], v[168:171], v[212:215], v[90:93]
	v_mfma_f32_16x16x32_bf16 v[78:81], v[160:163], v[220:223], v[78:81]
	v_mfma_f32_16x16x32_bf16 v[74:77], v[168:171], v[220:223], v[74:77]
	s_setprio 0
	s_setprio 1
	v_mfma_f32_16x16x32_bf16 v[118:121], v[176:179], v[192:195], v[118:121]
	v_mfma_f32_16x16x32_bf16 v[114:117], v[184:187], v[192:195], v[114:117]
	v_mfma_f32_16x16x32_bf16 v[102:105], v[176:179], v[200:203], v[102:105]
	v_mfma_f32_16x16x32_bf16 v[98:101], v[184:187], v[200:203], v[98:101]
	v_mfma_f32_16x16x32_bf16 v[86:89], v[176:179], v[208:211], v[86:89]
	v_mfma_f32_16x16x32_bf16 v[82:85], v[184:187], v[208:211], v[82:85]
	v_mfma_f32_16x16x32_bf16 v[70:73], v[176:179], v[216:219], v[70:73]
	v_mfma_f32_16x16x32_bf16 v[66:69], v[184:187], v[216:219], v[66:69]
	v_mfma_f32_16x16x32_bf16 v[118:121], v[180:183], v[196:199], v[118:121]
	v_mfma_f32_16x16x32_bf16 v[114:117], v[188:191], v[196:199], v[114:117]
	v_mfma_f32_16x16x32_bf16 v[102:105], v[180:183], v[204:207], v[102:105]
	v_mfma_f32_16x16x32_bf16 v[98:101], v[188:191], v[204:207], v[98:101]
	v_mfma_f32_16x16x32_bf16 v[86:89], v[180:183], v[212:215], v[86:89]
	v_mfma_f32_16x16x32_bf16 v[82:85], v[188:191], v[212:215], v[82:85]
	v_mfma_f32_16x16x32_bf16 v[70:73], v[180:183], v[220:223], v[70:73]
	v_mfma_f32_16x16x32_bf16 v[66:69], v[188:191], v[220:223], v[66:69]
	s_setprio 0
	s_barrier
	s_add_i32 s62, s44, s31
	v_lshl_add_u64 v[152:153], s[22:23], 0, v[136:137]
	s_mov_b32 m0, s62
	ds_read_b128 v[192:195], v158 offset:16384
	ds_read_b128 v[196:199], v158 offset:17408
	ds_read_b128 v[200:203], v158 offset:18432
	ds_read_b128 v[204:207], v158 offset:19456
	ds_read_b128 v[208:211], v158 offset:20480
	ds_read_b128 v[212:215], v158 offset:21504
	ds_read_b128 v[216:219], v158 offset:22528
	ds_read_b128 v[220:223], v158 offset:23552
	global_load_lds_dwordx4 v[152:153], off
	s_add_i32 m0, s62, 0x2000
	s_add_u32 s62, s22, 0x100000
	v_lshl_add_u64 v[172:173], s[22:23], 0, v[130:131]
	s_addc_u32 s63, s23, 0
	s_add_i32 s64, s45, s31
	global_load_lds_dwordx4 v[172:173], off
	v_lshl_add_u64 v[224:225], s[62:63], 0, v[136:137]
	s_mov_b32 m0, s64
	v_lshl_add_u64 v[226:227], s[24:25], 0, v[132:133]
	global_load_lds_dwordx4 v[224:225], off
	v_lshl_add_u64 v[224:225], s[62:63], 0, v[130:131]
	s_add_i32 m0, s64, 0x2000
	s_nop 0
	global_load_lds_dwordx4 v[224:225], off
	v_lshl_add_u64 v[224:225], s[24:25], 0, v[138:139]
	s_mov_b32 m0, s34
	s_nop 0
	global_load_lds_dwordx4 v[224:225], off
	s_mov_b32 m0, s35
	s_nop 0
	global_load_lds_dwordx4 v[226:227], off
	s_waitcnt lgkmcnt(0)
	v_mfma_f32_16x16x32_bf16 v[62:65], v[148:151], v[192:195], v[62:65]
	v_mfma_f32_16x16x32_bf16 v[58:61], v[164:167], v[192:195], v[58:61]
	v_mfma_f32_16x16x32_bf16 v[46:49], v[148:151], v[200:203], v[46:49]
	v_mfma_f32_16x16x32_bf16 v[42:45], v[164:167], v[200:203], v[42:45]
	s_waitcnt vmcnt(8)
	s_barrier
	s_setprio 1
	v_mfma_f32_16x16x32_bf16 v[30:33], v[148:151], v[208:211], v[30:33]
	v_mfma_f32_16x16x32_bf16 v[26:29], v[164:167], v[208:211], v[26:29]
	v_mfma_f32_16x16x32_bf16 v[14:17], v[148:151], v[216:219], v[14:17]
	v_mfma_f32_16x16x32_bf16 v[10:13], v[164:167], v[216:219], v[10:13]
	v_mfma_f32_16x16x32_bf16 v[62:65], v[160:163], v[196:199], v[62:65]
	v_mfma_f32_16x16x32_bf16 v[58:61], v[168:171], v[196:199], v[58:61]
	v_mfma_f32_16x16x32_bf16 v[46:49], v[160:163], v[204:207], v[46:49]
	v_mfma_f32_16x16x32_bf16 v[42:45], v[168:171], v[204:207], v[42:45]
	v_mfma_f32_16x16x32_bf16 v[30:33], v[160:163], v[212:215], v[30:33]
	v_mfma_f32_16x16x32_bf16 v[26:29], v[168:171], v[212:215], v[26:29]
	v_mfma_f32_16x16x32_bf16 v[14:17], v[160:163], v[220:223], v[14:17]
	v_mfma_f32_16x16x32_bf16 v[10:13], v[168:171], v[220:223], v[10:13]
	s_setprio 0
	s_setprio 1
	v_mfma_f32_16x16x32_bf16 v[54:57], v[176:179], v[192:195], v[54:57]
	v_mfma_f32_16x16x32_bf16 v[50:53], v[184:187], v[192:195], v[50:53]
	v_mfma_f32_16x16x32_bf16 v[38:41], v[176:179], v[200:203], v[38:41]
	v_mfma_f32_16x16x32_bf16 v[34:37], v[184:187], v[200:203], v[34:37]
	v_mfma_f32_16x16x32_bf16 v[22:25], v[176:179], v[208:211], v[22:25]
	v_mfma_f32_16x16x32_bf16 v[18:21], v[184:187], v[208:211], v[18:21]
	v_mfma_f32_16x16x32_bf16 v[6:9], v[176:179], v[216:219], v[6:9]
	v_mfma_f32_16x16x32_bf16 v[2:5], v[184:187], v[216:219], v[2:5]
	v_mfma_f32_16x16x32_bf16 v[54:57], v[180:183], v[196:199], v[54:57]
	v_mfma_f32_16x16x32_bf16 v[50:53], v[188:191], v[196:199], v[50:53]
	v_mfma_f32_16x16x32_bf16 v[38:41], v[180:183], v[204:207], v[38:41]
	v_mfma_f32_16x16x32_bf16 v[34:37], v[188:191], v[204:207], v[34:37]
	v_mfma_f32_16x16x32_bf16 v[22:25], v[180:183], v[212:215], v[22:25]
	v_mfma_f32_16x16x32_bf16 v[18:21], v[188:191], v[212:215], v[18:21]
	v_mfma_f32_16x16x32_bf16 v[6:9], v[180:183], v[220:223], v[6:9]
	v_mfma_f32_16x16x32_bf16 v[2:5], v[188:191], v[220:223], v[2:5]
	s_setprio 0
	s_barrier
	s_add_i32 s62, 0, 0x18000
	v_add_u32_e32 v159, s62, v135
	s_add_i32 s63, 0, 0x1c000
	ds_read_b128 v[148:151], v159
	ds_read_b128 v[160:163], v159 offset:1024
	ds_read_b128 v[164:167], v159 offset:2048
	ds_read_b128 v[168:171], v159 offset:3072
	v_add_u32_e32 v159, s63, v135
	ds_read_b128 v[176:179], v159
	ds_read_b128 v[180:183], v159 offset:1024
	ds_read_b128 v[184:187], v159 offset:2048
	ds_read_b128 v[188:191], v159 offset:3072
	s_add_u32 s24, s24, 0x100000
	s_addc_u32 s25, s25, 0
	s_mov_b32 m0, s36
	v_lshl_add_u64 v[228:229], s[24:25], 0, v[138:139]
	ds_read_b128 v[192:195], v158 offset:32768
	ds_read_b128 v[196:199], v158 offset:33792
	ds_read_b128 v[200:203], v158 offset:34816
	ds_read_b128 v[204:207], v158 offset:35840
	ds_read_b128 v[208:211], v158 offset:36864
	ds_read_b128 v[212:215], v158 offset:37888
	ds_read_b128 v[216:219], v158 offset:38912
	ds_read_b128 v[220:223], v158 offset:39936
	global_load_lds_dwordx4 v[228:229], off
	v_lshl_add_u64 v[228:229], s[24:25], 0, v[132:133]
	s_mov_b32 m0, s37
	s_nop 0
	global_load_lds_dwordx4 v[228:229], off
	s_waitcnt lgkmcnt(0)
	v_mfma_f32_16x16x32_bf16 v[126:129], v[148:151], v[192:195], v[126:129]
	v_mfma_f32_16x16x32_bf16 v[122:125], v[164:167], v[192:195], v[122:125]
	v_mfma_f32_16x16x32_bf16 v[110:113], v[148:151], v[200:203], v[110:113]
	v_mfma_f32_16x16x32_bf16 v[106:109], v[164:167], v[200:203], v[106:109]
	s_waitcnt vmcnt(8)
	s_barrier
	s_setprio 1
	v_mfma_f32_16x16x32_bf16 v[94:97], v[148:151], v[208:211], v[94:97]
	v_mfma_f32_16x16x32_bf16 v[90:93], v[164:167], v[208:211], v[90:93]
	v_mfma_f32_16x16x32_bf16 v[78:81], v[148:151], v[216:219], v[78:81]
	v_mfma_f32_16x16x32_bf16 v[74:77], v[164:167], v[216:219], v[74:77]
	v_mfma_f32_16x16x32_bf16 v[126:129], v[160:163], v[196:199], v[126:129]
	v_mfma_f32_16x16x32_bf16 v[122:125], v[168:171], v[196:199], v[122:125]
	v_mfma_f32_16x16x32_bf16 v[110:113], v[160:163], v[204:207], v[110:113]
	v_mfma_f32_16x16x32_bf16 v[106:109], v[168:171], v[204:207], v[106:109]
	v_mfma_f32_16x16x32_bf16 v[94:97], v[160:163], v[212:215], v[94:97]
	v_mfma_f32_16x16x32_bf16 v[90:93], v[168:171], v[212:215], v[90:93]
	v_mfma_f32_16x16x32_bf16 v[78:81], v[160:163], v[220:223], v[78:81]
	v_mfma_f32_16x16x32_bf16 v[74:77], v[168:171], v[220:223], v[74:77]
	s_setprio 0
	s_setprio 1
	v_mfma_f32_16x16x32_bf16 v[118:121], v[176:179], v[192:195], v[118:121]
	v_mfma_f32_16x16x32_bf16 v[114:117], v[184:187], v[192:195], v[114:117]
	v_mfma_f32_16x16x32_bf16 v[102:105], v[176:179], v[200:203], v[102:105]
	v_mfma_f32_16x16x32_bf16 v[98:101], v[184:187], v[200:203], v[98:101]
	v_mfma_f32_16x16x32_bf16 v[86:89], v[176:179], v[208:211], v[86:89]
	v_mfma_f32_16x16x32_bf16 v[82:85], v[184:187], v[208:211], v[82:85]
	v_mfma_f32_16x16x32_bf16 v[70:73], v[176:179], v[216:219], v[70:73]
	v_mfma_f32_16x16x32_bf16 v[66:69], v[184:187], v[216:219], v[66:69]
	v_mfma_f32_16x16x32_bf16 v[118:121], v[180:183], v[196:199], v[118:121]
	v_mfma_f32_16x16x32_bf16 v[114:117], v[188:191], v[196:199], v[114:117]
	v_mfma_f32_16x16x32_bf16 v[102:105], v[180:183], v[204:207], v[102:105]
	v_mfma_f32_16x16x32_bf16 v[98:101], v[188:191], v[204:207], v[98:101]
	v_mfma_f32_16x16x32_bf16 v[86:89], v[180:183], v[212:215], v[86:89]
	v_mfma_f32_16x16x32_bf16 v[82:85], v[188:191], v[212:215], v[82:85]
	v_mfma_f32_16x16x32_bf16 v[70:73], v[180:183], v[220:223], v[70:73]
	v_mfma_f32_16x16x32_bf16 v[66:69], v[188:191], v[220:223], v[66:69]
	s_setprio 0
	s_barrier
	s_add_i32 s24, s62, s31
	v_lshl_add_u64 v[152:153], v[152:153], 0, s[16:17]
	s_mov_b32 m0, s24
	ds_read_b128 v[192:195], v158 offset:49152
	ds_read_b128 v[196:199], v158 offset:50176
	ds_read_b128 v[200:203], v158 offset:51200
	ds_read_b128 v[204:207], v158 offset:52224
	ds_read_b128 v[208:211], v158 offset:53248
	ds_read_b128 v[212:215], v158 offset:54272
	ds_read_b128 v[216:219], v158 offset:55296
	ds_read_b128 v[220:223], v158 offset:56320
	global_load_lds_dwordx4 v[152:153], off
	s_add_i32 m0, s24, 0x2000
	s_add_u32 s22, s22, 0x100080
	v_lshl_add_u64 v[152:153], v[172:173], 0, s[16:17]
	s_addc_u32 s23, s23, 0
	s_add_i32 s24, s63, s31
	global_load_lds_dwordx4 v[152:153], off
	v_lshl_add_u64 v[152:153], s[22:23], 0, v[136:137]
	s_mov_b32 m0, s24
	s_nop 0
	global_load_lds_dwordx4 v[152:153], off
	v_lshl_add_u64 v[152:153], s[22:23], 0, v[130:131]
	s_add_i32 m0, s24, 0x2000
	s_nop 0
	global_load_lds_dwordx4 v[152:153], off
	v_lshl_add_u64 v[152:153], v[224:225], 0, s[16:17]
	s_mov_b32 m0, s40
	s_nop 0
	global_load_lds_dwordx4 v[152:153], off
	v_lshl_add_u64 v[152:153], v[226:227], 0, s[16:17]
	s_mov_b32 m0, s41
	s_nop 0
	global_load_lds_dwordx4 v[152:153], off
	s_waitcnt lgkmcnt(0)
	v_mfma_f32_16x16x32_bf16 v[62:65], v[148:151], v[192:195], v[62:65]
	v_mfma_f32_16x16x32_bf16 v[58:61], v[164:167], v[192:195], v[58:61]
	v_mfma_f32_16x16x32_bf16 v[46:49], v[148:151], v[200:203], v[46:49]
	v_mfma_f32_16x16x32_bf16 v[42:45], v[164:167], v[200:203], v[42:45]
	s_waitcnt vmcnt(8)
	s_barrier
	s_setprio 1
	v_mfma_f32_16x16x32_bf16 v[30:33], v[148:151], v[208:211], v[30:33]
	v_mfma_f32_16x16x32_bf16 v[26:29], v[164:167], v[208:211], v[26:29]
	v_mfma_f32_16x16x32_bf16 v[14:17], v[148:151], v[216:219], v[14:17]
	v_mfma_f32_16x16x32_bf16 v[10:13], v[164:167], v[216:219], v[10:13]
	v_mfma_f32_16x16x32_bf16 v[62:65], v[160:163], v[196:199], v[62:65]
	v_mfma_f32_16x16x32_bf16 v[58:61], v[168:171], v[196:199], v[58:61]
	v_mfma_f32_16x16x32_bf16 v[46:49], v[160:163], v[204:207], v[46:49]
	v_mfma_f32_16x16x32_bf16 v[42:45], v[168:171], v[204:207], v[42:45]
	v_mfma_f32_16x16x32_bf16 v[30:33], v[160:163], v[212:215], v[30:33]
	v_mfma_f32_16x16x32_bf16 v[26:29], v[168:171], v[212:215], v[26:29]
	v_mfma_f32_16x16x32_bf16 v[14:17], v[160:163], v[220:223], v[14:17]
	v_mfma_f32_16x16x32_bf16 v[10:13], v[168:171], v[220:223], v[10:13]
	s_setprio 0
	s_setprio 1
	v_mfma_f32_16x16x32_bf16 v[54:57], v[176:179], v[192:195], v[54:57]
	v_mfma_f32_16x16x32_bf16 v[50:53], v[184:187], v[192:195], v[50:53]
	v_mfma_f32_16x16x32_bf16 v[38:41], v[176:179], v[200:203], v[38:41]
	v_mfma_f32_16x16x32_bf16 v[34:37], v[184:187], v[200:203], v[34:37]
	v_mfma_f32_16x16x32_bf16 v[22:25], v[176:179], v[208:211], v[22:25]
	v_mfma_f32_16x16x32_bf16 v[18:21], v[184:187], v[208:211], v[18:21]
	v_mfma_f32_16x16x32_bf16 v[6:9], v[176:179], v[216:219], v[6:9]
	v_mfma_f32_16x16x32_bf16 v[2:5], v[184:187], v[216:219], v[2:5]
	v_mfma_f32_16x16x32_bf16 v[54:57], v[180:183], v[196:199], v[54:57]
	v_mfma_f32_16x16x32_bf16 v[50:53], v[188:191], v[196:199], v[50:53]
	v_mfma_f32_16x16x32_bf16 v[38:41], v[180:183], v[204:207], v[38:41]
	v_mfma_f32_16x16x32_bf16 v[34:37], v[188:191], v[204:207], v[34:37]
	v_mfma_f32_16x16x32_bf16 v[22:25], v[180:183], v[212:215], v[22:25]
	v_mfma_f32_16x16x32_bf16 v[18:21], v[188:191], v[212:215], v[18:21]
	v_mfma_f32_16x16x32_bf16 v[6:9], v[180:183], v[220:223], v[6:9]
	v_mfma_f32_16x16x32_bf16 v[2:5], v[188:191], v[220:223], v[2:5]
	s_setprio 0
	s_barrier
	s_add_i32 s61, s61, 2
	s_add_u32 s0, s0, 0x100
	s_addc_u32 s1, s1, 0
	s_add_u32 s59, s59, 0x100
	s_addc_u32 s60, s60, 0
	s_cmp_gt_u32 s61, 61
	s_cbranch_scc0 .LBB0_731
	v_and_b32_e32 v165, 3, v174
	v_lshrrev_b32_e32 v170, 2, v174
	v_lshlrev_b32_e32 v164, 6, v165
	v_and_or_b32 v164, v174, 60, v164
	v_and_b32_e32 v171, 15, v174
	v_sub_u32_e32 v170, v170, v171
	v_lshrrev_b32_e32 v171, 4, v174
	v_sub_u32_e32 v165, v165, v171
	v_mul_i32_i24_e32 v170, 0xac00, v170
	v_lshl_add_u32 v166, v165, 4, v170
	v_ashrrev_i32_e32 v167, 31, v166
	s_lshl_b32 s5, s56, 8
	s_add_i32 s5, s5, s39
	v_or_b32_e32 v159, s5, v1
	v_cmp_lt_i32_e64 s[0:1], s46, v159
	s_and_b64 s[22:23], s[0:1], s[18:19]
	v_mov_b64_e32 v[150:151], 0
	s_and_saveexec_b64 s[0:1], s[22:23]
	v_add_u32_e32 v148, 0xffffe000, v159
	v_lshrrev_b32_e32 v148, 2, v148
	v_and_b32_e32 v148, 0x3ffffff2, v148
	v_add_u32_e32 v150, v148, v154
	v_mov_b64_e32 v[148:149], s[10:11]
	v_mad_u64_u32 v[150:151], s[22:23], v150, s47, v[148:149]
	s_or_b64 exec, exec, s[0:1]
	v_lshl_or_b32 v148, s55, 8, v155
	v_mov_b64_e32 v[152:153], s[6:7]
	v_ashrrev_i32_e32 v149, 31, v148
	v_mad_i64_i32 v[152:153], s[0:1], v159, s48, v[152:153]
	v_lshl_add_u64 v[152:153], v[148:149], 1, v[152:153]
	v_cmp_ne_u64_e64 s[0:1], 0, v[150:151]
	v_lshl_add_u64 v[150:151], v[148:149], 2, v[150:151]
	v_cvt_pk_bf16_f32 v160, v126, v127
	v_cvt_pk_bf16_f32 v161, v128, v129
	v_cvt_pk_bf16_f32 v162, v122, v123
	v_cvt_pk_bf16_f32 v163, v124, v125
	ds_bpermute_b32 v160, v164, v160
	ds_bpermute_b32 v161, v164, v161
	ds_bpermute_b32 v162, v164, v162
	ds_bpermute_b32 v163, v164, v163
	v_lshl_add_u64 v[168:169], v[166:167], 0, v[152:153]
	s_waitcnt lgkmcnt(0)
	global_store_dwordx4 v[168:169], v[160:163], off
	s_and_saveexec_b64 s[22:23], s[0:1]
	s_cbranch_execz .LBB0_736
	global_store_dwordx4 v[150:151], v[126:129], off
	global_store_dwordx4 v[150:151], v[122:125], off offset:16
